# grid-barrier invalidate now issued by wave 1 right after the arrival s_barrier (runs beside wave 0 arrive/release protocol); rest as previous version
# speedup vs baseline: 1.0101x; 1.0020x over previous
.LBB0_70:
	s_cmp_gt_i32 s95, 1
	s_cselect_b64 s[6:7], -1, 0
	s_and_b64 s[0:1], s[20:21], s[6:7]
	s_andn2_b64 vcc, exec, s[0:1]
	v_cmp_eq_u32_e64 s[0:1], 0, v129
	s_cbranch_vccnz .LBB0_121
	s_waitcnt vmcnt(0)
	s_barrier
	v_readlane_b32 s98, v251, 24
	s_nop 3
	s_cmp_eq_u32 s98, 1
	s_cbranch_scc0 .Lmy_einv_0
	buffer_inv sc1
.Lmy_einv_0:
	s_and_saveexec_b64 s[4:5], s[0:1]
	s_cbranch_execz .LBB0_120
	s_add_i32 s0, 0, 0x27f00
	s_waitcnt vmcnt(15)
	v_mov_b32_e32 v0, s0
	s_waitcnt vmcnt(0) expcnt(0) lgkmcnt(0)
	ds_read_b32 v2, v0
	s_add_i32 s0, 0, 0x27f04
	v_mov_b32_e32 v0, s0
	ds_read_b32 v0, v0
	s_waitcnt lgkmcnt(1)
	v_cmp_ne_u32_e32 vcc, 0, v2
	s_cbranch_vccnz .LBB0_88
	v_readlane_b32 s0, v251, 1
	v_readlane_b32 s1, v251, 2
	s_load_dwordx2 s[2:3], s[0:1], 0x4
	s_add_u32 s0, s92, 0x2a0200
	s_addc_u32 s1, s93, 0
	s_add_u32 s8, s92, 0x2a0400
	s_addc_u32 s9, s93, 0
	s_add_u32 s14, s92, 0x2a0500
	s_addc_u32 s15, s93, 0
	s_add_u32 s18, s92, 0x2a0600
	s_addc_u32 s19, s93, 0
	s_add_u32 s20, s92, 0x2a0700
	s_addc_u32 s21, s93, 0
	s_add_u32 s22, s92, 0x2a0800
	s_addc_u32 s23, s93, 0
	s_add_u32 s24, s92, 0x2a0900
	s_addc_u32 s25, s93, 0
	s_add_u32 s26, s92, 0x2a0a00
	s_addc_u32 s27, s93, 0
	s_add_u32 s28, s92, 0x2a0b00
	s_addc_u32 s29, s93, 0
	s_add_u32 s30, s92, 0x2a0c00
	s_addc_u32 s31, s93, 0
	s_add_u32 s34, s92, 0x2a0d00
	s_addc_u32 s35, s93, 0
	s_add_u32 s36, s92, 0x2a0e00
	s_addc_u32 s37, s93, 0
	s_add_u32 s38, s92, 0x2a0f00
	s_addc_u32 s39, s93, 0
	s_add_u32 s40, s92, 0x2a1000
	s_addc_u32 s41, s93, 0
	s_add_u32 s42, s92, 0x2a1100
	s_addc_u32 s43, s93, 0
	s_add_u32 s44, s92, 0x2a1200
	s_addc_u32 s45, s93, 0
	s_waitcnt lgkmcnt(0)
	s_mul_i32 s2, s2, s96
	s_add_u32 s46, s92, 0x2a1300
	s_mul_i32 s2, s2, s3
	s_addc_u32 s47, s93, 0
	s_mov_b32 s3, 1
	v_mov_b32_e32 v16, 0
	s_branch .LBB0_75

.LBB0_120:
	s_or_b64 exec, exec, s[4:5]
	s_waitcnt vmcnt(0) lgkmcnt(0)
	s_barrier

.LBB0_138:
	s_cmp_gt_i32 s95, 2
	s_cselect_b64 s[0:1], -1, 0
	s_and_b64 s[2:3], s[4:5], s[0:1]
	s_andn2_b64 vcc, exec, s[2:3]
	s_cbranch_vccnz .LBB0_188
	s_waitcnt vmcnt(0)
	v_cmp_eq_u32_e32 vcc, 0, v129
	s_barrier
	v_readlane_b32 s98, v251, 24
	s_nop 3
	s_cmp_eq_u32 s98, 1
	s_cbranch_scc0 .Lmy_einv_1
	buffer_inv sc1
.Lmy_einv_1:
	s_and_saveexec_b64 s[4:5], vcc
	s_cbranch_execz .LBB0_187
	s_add_i32 s2, 0, 0x27f00
	s_waitcnt vmcnt(15)
	v_mov_b32_e32 v0, s2
	s_waitcnt vmcnt(0) expcnt(0) lgkmcnt(0)
	ds_read_b32 v2, v0
	s_add_i32 s2, 0, 0x27f04
	v_mov_b32_e32 v0, s2
	ds_read_b32 v0, v0
	s_waitcnt lgkmcnt(1)
	v_cmp_ne_u32_e32 vcc, 0, v2
	s_cbranch_vccnz .LBB0_155
	v_readlane_b32 s6, v251, 1
	v_readlane_b32 s7, v251, 2
	s_load_dwordx2 s[2:3], s[6:7], 0x4
	s_add_u32 s6, s92, 0x2a0200
	s_addc_u32 s7, s93, 0
	s_add_u32 s8, s92, 0x2a0400
	s_addc_u32 s9, s93, 0
	s_add_u32 s14, s92, 0x2a0500
	s_addc_u32 s15, s93, 0
	s_add_u32 s18, s92, 0x2a0600
	s_addc_u32 s19, s93, 0
	s_add_u32 s20, s92, 0x2a0700
	s_addc_u32 s21, s93, 0
	s_add_u32 s22, s92, 0x2a0800
	s_addc_u32 s23, s93, 0
	s_add_u32 s24, s92, 0x2a0900
	s_addc_u32 s25, s93, 0
	s_add_u32 s26, s92, 0x2a0a00
	s_addc_u32 s27, s93, 0
	s_add_u32 s28, s92, 0x2a0b00
	s_addc_u32 s29, s93, 0
	s_add_u32 s30, s92, 0x2a0c00
	s_addc_u32 s31, s93, 0
	s_add_u32 s34, s92, 0x2a0d00
	s_addc_u32 s35, s93, 0
	s_add_u32 s36, s92, 0x2a0e00
	s_addc_u32 s37, s93, 0
	s_add_u32 s38, s92, 0x2a0f00
	s_addc_u32 s39, s93, 0
	s_add_u32 s40, s92, 0x2a1000
	s_addc_u32 s41, s93, 0
	s_add_u32 s42, s92, 0x2a1100
	s_addc_u32 s43, s93, 0
	s_add_u32 s44, s92, 0x2a1200
	s_addc_u32 s45, s93, 0
	s_waitcnt lgkmcnt(0)
	s_mul_i32 s2, s2, s96
	s_add_u32 s46, s92, 0x2a1300
	s_mul_i32 s2, s2, s3
	s_addc_u32 s47, s93, 0
	s_mov_b32 s3, 1
	v_mov_b32_e32 v16, 0
	s_branch .LBB0_143

.LBB0_276:
	s_cmp_gt_i32 s95, 3
	s_cselect_b64 s[0:1], -1, 0
	s_and_b64 s[2:3], s[8:9], s[0:1]
	s_andn2_b64 vcc, exec, s[2:3]
	s_cbranch_vccnz .LBB0_326
	s_waitcnt vmcnt(0)
	v_cmp_eq_u32_e32 vcc, 0, v129
	s_barrier
	v_readlane_b32 s98, v251, 24
	s_nop 3
	s_cmp_eq_u32 s98, 1
	s_cbranch_scc0 .Lmy_einv_2
	buffer_inv sc1
.Lmy_einv_2:
	s_and_saveexec_b64 s[4:5], vcc
	s_cbranch_execz .LBB0_325
	s_add_i32 s2, 0, 0x27f00
	s_waitcnt vmcnt(15)
	v_mov_b32_e32 v0, s2
	s_waitcnt vmcnt(0) expcnt(0) lgkmcnt(0)
	ds_read_b32 v2, v0
	s_add_i32 s2, 0, 0x27f04
	v_mov_b32_e32 v0, s2
	ds_read_b32 v0, v0
	s_waitcnt lgkmcnt(1)
	v_cmp_ne_u32_e32 vcc, 0, v2
	s_cbranch_vccnz .LBB0_293
	v_readlane_b32 s6, v251, 1
	v_readlane_b32 s7, v251, 2
	s_load_dwordx2 s[2:3], s[6:7], 0x4
	s_add_u32 s6, s92, 0x2a0200
	s_addc_u32 s7, s93, 0
	s_add_u32 s8, s92, 0x2a0400
	s_addc_u32 s9, s93, 0
	s_add_u32 s10, s92, 0x2a0500
	s_addc_u32 s11, s93, 0
	s_add_u32 s12, s92, 0x2a0600
	s_addc_u32 s13, s93, 0
	s_add_u32 s14, s92, 0x2a0700
	s_addc_u32 s15, s93, 0
	s_add_u32 s16, s92, 0x2a0800
	s_addc_u32 s17, s93, 0
	s_add_u32 s18, s92, 0x2a0900
	s_addc_u32 s19, s93, 0
	s_add_u32 s20, s92, 0x2a0a00
	s_addc_u32 s21, s93, 0
	s_add_u32 s22, s92, 0x2a0b00
	s_addc_u32 s23, s93, 0
	s_add_u32 s24, s92, 0x2a0c00
	s_addc_u32 s25, s93, 0
	s_add_u32 s26, s92, 0x2a0d00
	s_addc_u32 s27, s93, 0
	s_add_u32 s28, s92, 0x2a0e00
	s_addc_u32 s29, s93, 0
	s_add_u32 s30, s92, 0x2a0f00
	s_addc_u32 s31, s93, 0
	s_add_u32 s34, s92, 0x2a1000
	s_addc_u32 s35, s93, 0
	s_add_u32 s36, s92, 0x2a1100
	s_addc_u32 s37, s93, 0
	s_add_u32 s38, s92, 0x2a1200
	s_addc_u32 s39, s93, 0
	s_waitcnt lgkmcnt(0)
	s_mul_i32 s2, s2, s96
	s_add_u32 s40, s92, 0x2a1300
	s_mul_i32 s2, s2, s3
	s_addc_u32 s41, s93, 0
	s_mov_b32 s3, 1
	v_mov_b32_e32 v16, 0
	s_branch .LBB0_281

.LBB0_337:
	s_cmp_gt_i32 s95, 4
	s_cselect_b64 s[0:1], -1, 0
	s_and_b64 s[2:3], s[6:7], s[0:1]
	s_andn2_b64 vcc, exec, s[2:3]
	s_cbranch_vccnz .LBB0_387
	s_waitcnt vmcnt(0)
	v_cmp_eq_u32_e32 vcc, 0, v129
	s_barrier
	v_readlane_b32 s98, v251, 24
	s_nop 3
	s_cmp_eq_u32 s98, 1
	s_cbranch_scc0 .Lmy_einv_3
	buffer_inv sc1
.Lmy_einv_3:
	s_and_saveexec_b64 s[4:5], vcc
	s_cbranch_execz .LBB0_386
	s_add_i32 s2, 0, 0x27f00
	v_mov_b32_e32 v64, s2
	s_waitcnt vmcnt(0) expcnt(0) lgkmcnt(0)
	ds_read_b32 v66, v64
	s_add_i32 s2, 0, 0x27f04
	v_mov_b32_e32 v64, s2
	ds_read_b32 v64, v64
	s_waitcnt lgkmcnt(1)
	v_cmp_ne_u32_e32 vcc, 0, v66
	s_cbranch_vccnz .LBB0_354
	v_readlane_b32 s6, v251, 1
	v_readlane_b32 s7, v251, 2
	s_load_dwordx2 s[2:3], s[6:7], 0x4
	s_add_u32 s6, s92, 0x2a0200
	s_addc_u32 s7, s93, 0
	s_add_u32 s10, s92, 0x2a0400
	s_addc_u32 s11, s93, 0
	s_add_u32 s12, s92, 0x2a0500
	s_addc_u32 s13, s93, 0
	s_add_u32 s14, s92, 0x2a0600
	s_addc_u32 s15, s93, 0
	s_add_u32 s16, s92, 0x2a0700
	s_addc_u32 s17, s93, 0
	s_add_u32 s18, s92, 0x2a0800
	s_addc_u32 s19, s93, 0
	s_add_u32 s20, s92, 0x2a0900
	s_addc_u32 s21, s93, 0
	s_add_u32 s22, s92, 0x2a0a00
	s_addc_u32 s23, s93, 0
	s_add_u32 s24, s92, 0x2a0b00
	s_addc_u32 s25, s93, 0
	s_add_u32 s26, s92, 0x2a0c00
	s_addc_u32 s27, s93, 0
	s_add_u32 s28, s92, 0x2a0d00
	s_addc_u32 s29, s93, 0
	s_add_u32 s30, s92, 0x2a0e00
	s_addc_u32 s31, s93, 0
	s_add_u32 s34, s92, 0x2a0f00
	s_addc_u32 s35, s93, 0
	s_add_u32 s36, s92, 0x2a1000
	s_addc_u32 s37, s93, 0
	s_add_u32 s38, s92, 0x2a1100
	s_addc_u32 s39, s93, 0
	s_add_u32 s40, s92, 0x2a1200
	s_addc_u32 s41, s93, 0
	s_waitcnt lgkmcnt(0)
	s_mul_i32 s2, s2, s96
	s_add_u32 s42, s92, 0x2a1300
	s_mul_i32 s2, s2, s3
	s_addc_u32 s43, s93, 0
	s_mov_b32 s3, 1
	v_mov_b32_e32 v80, 0
	s_branch .LBB0_342

.LBB0_519:
	s_cmp_gt_i32 s95, 5
	s_cselect_b64 s[0:1], -1, 0
	s_and_b64 s[2:3], s[40:41], s[0:1]
	s_andn2_b64 vcc, exec, s[2:3]
	s_cbranch_vccnz .LBB0_569
	s_waitcnt vmcnt(0)
	v_cmp_eq_u32_e32 vcc, 0, v129
	s_barrier
	v_readlane_b32 s98, v251, 24
	s_nop 3
	s_cmp_eq_u32 s98, 1
	s_cbranch_scc0 .Lmy_einv_4
	buffer_inv sc1

.LBB0_611:
	s_cmp_gt_i32 s95, 6
	s_cselect_b64 s[0:1], -1, 0
	s_and_b64 s[2:3], s[6:7], s[0:1]
	s_andn2_b64 vcc, exec, s[2:3]
	s_cbranch_vccnz .LBB0_661
	s_waitcnt vmcnt(0)
	v_cmp_eq_u32_e32 vcc, 0, v129
	s_barrier
	v_readlane_b32 s98, v251, 24
	s_nop 3
	s_cmp_eq_u32 s98, 1
	s_cbranch_scc0 .Lmy_einv_5
	buffer_inv sc1

.LBB0_700:
	s_cmp_gt_i32 s95, 7
	s_cselect_b64 s[0:1], -1, 0
	s_and_b64 s[2:3], s[4:5], s[0:1]
	s_andn2_b64 vcc, exec, s[2:3]
	s_cbranch_vccnz .LBB0_750
	s_waitcnt vmcnt(0)
	v_cmp_eq_u32_e32 vcc, 0, v129
	s_barrier
	v_readlane_b32 s98, v251, 24
	s_nop 3
	s_cmp_eq_u32 s98, 1
	s_cbranch_scc0 .Lmy_einv_6
	buffer_inv sc1

	.amdhsa_kernel _Z9hymba_fwd4Args
		.amdhsa_group_segment_fixed_size 0
		.amdhsa_private_segment_fixed_size 0
		.amdhsa_kernarg_size 416
		.amdhsa_user_sgpr_count 2
		.amdhsa_user_sgpr_dispatch_ptr 0
		.amdhsa_user_sgpr_queue_ptr 0
		.amdhsa_user_sgpr_kernarg_segment_ptr 1
		.amdhsa_user_sgpr_dispatch_id 0
		.amdhsa_user_sgpr_kernarg_preload_length 0
		.amdhsa_user_sgpr_kernarg_preload_offset 0
		.amdhsa_user_sgpr_private_segment_size 0
		.amdhsa_uses_dynamic_stack 0
		.amdhsa_enable_private_segment 0
		.amdhsa_system_sgpr_workgroup_id_x 1
		.amdhsa_system_sgpr_workgroup_id_y 0
		.amdhsa_system_sgpr_workgroup_id_z 0
		.amdhsa_system_sgpr_workgroup_info 0
		.amdhsa_system_vgpr_workitem_id 2
		.amdhsa_next_free_vgpr 252
		.amdhsa_next_free_sgpr 100
		.amdhsa_accum_offset 252
		.amdhsa_reserve_vcc 1
		.amdhsa_float_round_mode_32 0
		.amdhsa_float_round_mode_16_64 0
		.amdhsa_float_denorm_mode_32 3
		.amdhsa_float_denorm_mode_16_64 3
		.amdhsa_dx10_clamp 1
		.amdhsa_ieee_mode 1
		.amdhsa_fp16_overflow 0
		.amdhsa_tg_split 0
		.amdhsa_exception_fp_ieee_invalid_op 0
		.amdhsa_exception_fp_denorm_src 0
		.amdhsa_exception_fp_ieee_div_zero 0
		.amdhsa_exception_fp_ieee_overflow 0
		.amdhsa_exception_fp_ieee_underflow 0
		.amdhsa_exception_fp_ieee_inexact 0
		.amdhsa_exception_int_div_zero 0
	.end_amdhsa_kernel

amdhsa.kernels:
  - .agpr_count:     0
    .args:
      - .offset:         0
        .size:           160
        .value_kind:     by_value
      - .offset:         160
        .size:           4
        .value_kind:     hidden_block_count_x
      - .offset:         164
        .size:           4
        .value_kind:     hidden_block_count_y
      - .offset:         168
        .size:           4
        .value_kind:     hidden_block_count_z
      - .offset:         172
        .size:           2
        .value_kind:     hidden_group_size_x
      - .offset:         174
        .size:           2
        .value_kind:     hidden_group_size_y
      - .offset:         176
        .size:           2
        .value_kind:     hidden_group_size_z
      - .offset:         178
        .size:           2
        .value_kind:     hidden_remainder_x
      - .offset:         180
        .size:           2
        .value_kind:     hidden_remainder_y
      - .offset:         182
        .size:           2
        .value_kind:     hidden_remainder_z
      - .offset:         200
        .size:           8
        .value_kind:     hidden_global_offset_x
      - .offset:         208
        .size:           8
        .value_kind:     hidden_global_offset_y
      - .offset:         216
        .size:           8
        .value_kind:     hidden_global_offset_z
      - .offset:         224
        .size:           2
        .value_kind:     hidden_grid_dims
      - .offset:         248
        .size:           8
        .value_kind:     hidden_multigrid_sync_arg
      - .offset:         280
        .size:           4
        .value_kind:     hidden_dynamic_lds_size
    .group_segment_fixed_size: 0
    .kernarg_segment_align: 8
    .kernarg_segment_size: 416
    .language:       OpenCL C
    .language_version:
      - 2
      - 0
    .max_flat_workgroup_size: 512
    .name:           _Z9hymba_fwd4Args
    .private_segment_fixed_size: 0
    .sgpr_count:     106
    .sgpr_spill_count: 83
    .symbol:         _Z9hymba_fwd4Args.kd
    .uniform_work_group_size: 1
    .uses_dynamic_stack: false
    .vgpr_count:     252
    .vgpr_spill_count: 0
    .wavefront_size: 64
